# loop-edge: MFMA segments of the GEMM K-loops - priority raise moved before the opening barrier, redundant lgkmcnt(0) after it dropped, priority drop moved after the closing barrier, mid-segment 0/1 fl
# baseline (speedup 1.0000x reference)
; #define PG8_STAGE(bufoff, gbase, voff) do { _Pragma("unroll") for (int _i = 0; _i < 2; ++_i) \
;         __builtin_amdgcn_global_load_lds((const unsigned*)((const char*)(gbase) + (voff)[_i]), (LAS unsigned*)(lds + (bufoff) + ldsw + _i * 8192), 16, 0, 0); } while (0)
; #define PG8_LDA(dst, b, h) do { _Pragma("unroll") for (int m = 0; m < 4; ++m) _Pragma("unroll") for (int k = 0; k < 2; ++k) dst[m][k] = *(const LAS bf16x8*)(lds + PG8_SA(b, h) + aoff + m * 2048 + k * 1024); } while (0)
; #define PG8_LDB(dst, b, h) do { _Pragma("unroll") for (int n = 0; n < 2; ++n) _Pragma("unroll") for (int k = 0; k < 2; ++k) dst[n][k] = *(const LAS bf16x8*)(lds + PG8_SB(b, h) + boff + n * 2048 + k * 1024); } while (0)
; #define PG8_MMA(ai, bj, At, Bt) do { __builtin_amdgcn_s_setprio(1); _Pragma("unroll") for (int m = 0; m < 4; ++m) _Pragma("unroll") for (int n = 0; n < 2; ++n) _Pragma("unroll") for (int k = 0; k < 2; ++k) \
;         acc[ai][bj][m][n] = __builtin_amdgcn_mfma_f32_16x16x32_bf16(Bt[n][k], At[m][k], acc[ai][bj][m][n], 0, 0, 0); __builtin_amdgcn_s_setprio(0); } while (0)
; #define PG8_WAIT_V(n) asm volatile("s_waitcnt vmcnt(" #n ")" ::: "memory")
; #define PG8_WAIT_L(n) asm volatile("s_waitcnt lgkmcnt(" #n ")" ::: "memory")
; #define PG8_BAR __builtin_amdgcn_s_barrier()
; #define PG8_SCHED __builtin_amdgcn_sched_barrier(0)
; template <class Epi, class Sched>
; __device__ __forceinline__ void gemm_stream(LAS unsigned char* lds, const int lda, const int ldb, const Sched& S, const Epi& E, const int wv) {
;     ...
;         for (int t = 0; t < nt; t += 2) {
;             const bool last = (t == nt - 2);
;             const char* a1 = cA + (size_t)(t + 1) * kstep;
;             const char* a2 = last ? nA : cA + (size_t)(t + 2) * kstep; const char* b2 = last ? nB : cB + (size_t)(t + 2) * kstep;
;             const char* a3 = a2 + kstep; const char* b3 = b2 + kstep;
;             PG8_LDB(B0, 0, 0); PG8_LDB(B1, 0, 1); PG8_SCHED; PG8_LDA(At, 0, 0); PG8_STAGE(PG8_SA(1, 1), a1 + hstepA, voffA);
;             PG8_WAIT_V(8); PG8_WAIT_L(0); PG8_BAR; PG8_MMA(0, 0, At, B0); PG8_MMA(0, 1, At, B1); PG8_BAR; PG8_SCHED;
;             PG8_LDA(At, 0, 1); PG8_STAGE(PG8_SB(0, 0), b2, voffB); PG8_STAGE(PG8_SB(0, 1), b2 + hstepB, voffB); PG8_STAGE(PG8_SA(0, 0), a2, voffA);
;             PG8_WAIT_V(8); PG8_WAIT_L(0); PG8_BAR; PG8_MMA(1, 0, At, B0); PG8_MMA(1, 1, At, B1); PG8_BAR; PG8_SCHED;
.LBB0_222:
	s_add_u32 s30, s28, 0xfff80080
	s_addc_u32 s31, s29, -1
	s_add_i32 s38, 0, 0x10000
	s_cmp_eq_u32 s37, 28
	s_cselect_b32 s35, s3, s31
	s_cselect_b32 s34, s21, s30
	s_cselect_b32 s31, s23, s36
	s_cselect_b32 s30, s27, s33
	s_add_i32 s59, 0, 0x14000
	v_add_u32_e32 v140, s38, v163
	v_add_u32_e32 v160, s59, v163
	ds_read_b128 v[128:131], v140
	ds_read_b128 v[132:135], v140 offset:1024
	ds_read_b128 v[136:139], v140 offset:2048
	ds_read_b128 v[140:143], v140 offset:3072
	ds_read_b128 v[156:159], v160
	ds_read_b128 v[166:169], v160 offset:1024
	ds_read_b128 v[170:173], v160 offset:2048
	ds_read_b128 v[174:177], v160 offset:3072
	v_lshl_add_u64 v[160:161], s[28:29], 0, v[152:153]
	s_add_i32 m0, s42, 0xc000
	ds_read_b128 v[178:181], v164
	ds_read_b128 v[182:185], v164 offset:1024
	ds_read_b128 v[186:189], v164 offset:2048
	ds_read_b128 v[190:193], v164 offset:3072
	ds_read_b128 v[200:203], v164 offset:4096
	ds_read_b128 v[204:207], v164 offset:5120
	ds_read_b128 v[208:211], v164 offset:6144
	ds_read_b128 v[212:215], v164 offset:7168
	global_load_lds_dwordx4 v[160:161], off
	v_lshl_add_u64 v[160:161], s[28:29], 0, v[154:155]
	s_add_i32 m0, s42, 0xe000
	s_nop 0
	global_load_lds_dwordx4 v[160:161], off
	s_waitcnt vmcnt(8)
	s_waitcnt lgkmcnt(0)
	s_setprio 1
	s_barrier
	v_mfma_f32_16x16x32_bf16 v[124:127], v[128:131], v[178:181], v[124:127]
	v_mfma_f32_16x16x32_bf16 v[120:123], v[136:139], v[178:181], v[120:123]
	v_mfma_f32_16x16x32_bf16 v[108:111], v[128:131], v[186:189], v[108:111]
	v_mfma_f32_16x16x32_bf16 v[104:107], v[136:139], v[186:189], v[104:107]
	v_mfma_f32_16x16x32_bf16 v[92:95], v[128:131], v[200:203], v[92:95]
	v_mfma_f32_16x16x32_bf16 v[88:91], v[136:139], v[200:203], v[88:91]
	v_mfma_f32_16x16x32_bf16 v[76:79], v[128:131], v[208:211], v[76:79]
	v_mfma_f32_16x16x32_bf16 v[72:75], v[136:139], v[208:211], v[72:75]
	v_mfma_f32_16x16x32_bf16 v[124:127], v[132:135], v[182:185], v[124:127]
	v_mfma_f32_16x16x32_bf16 v[120:123], v[140:143], v[182:185], v[120:123]
	v_mfma_f32_16x16x32_bf16 v[108:111], v[132:135], v[190:193], v[108:111]
	v_mfma_f32_16x16x32_bf16 v[104:107], v[140:143], v[190:193], v[104:107]
	v_mfma_f32_16x16x32_bf16 v[92:95], v[132:135], v[204:207], v[92:95]
	v_mfma_f32_16x16x32_bf16 v[88:91], v[140:143], v[204:207], v[88:91]
	v_mfma_f32_16x16x32_bf16 v[76:79], v[132:135], v[212:215], v[76:79]
	v_mfma_f32_16x16x32_bf16 v[72:75], v[140:143], v[212:215], v[72:75]
	v_mfma_f32_16x16x32_bf16 v[116:119], v[156:159], v[178:181], v[116:119]
	v_mfma_f32_16x16x32_bf16 v[112:115], v[170:173], v[178:181], v[112:115]
	v_mfma_f32_16x16x32_bf16 v[100:103], v[156:159], v[186:189], v[100:103]
	v_mfma_f32_16x16x32_bf16 v[96:99], v[170:173], v[186:189], v[96:99]
	v_mfma_f32_16x16x32_bf16 v[84:87], v[156:159], v[200:203], v[84:87]
	v_mfma_f32_16x16x32_bf16 v[80:83], v[170:173], v[200:203], v[80:83]
	v_mfma_f32_16x16x32_bf16 v[68:71], v[156:159], v[208:211], v[68:71]
	v_mfma_f32_16x16x32_bf16 v[64:67], v[170:173], v[208:211], v[64:67]
	v_mfma_f32_16x16x32_bf16 v[116:119], v[166:169], v[182:185], v[116:119]
	v_mfma_f32_16x16x32_bf16 v[112:115], v[174:177], v[182:185], v[112:115]
	v_mfma_f32_16x16x32_bf16 v[100:103], v[166:169], v[190:193], v[100:103]
	v_mfma_f32_16x16x32_bf16 v[96:99], v[174:177], v[190:193], v[96:99]
	v_mfma_f32_16x16x32_bf16 v[84:87], v[166:169], v[204:207], v[84:87]
	v_mfma_f32_16x16x32_bf16 v[80:83], v[174:177], v[204:207], v[80:83]
	v_mfma_f32_16x16x32_bf16 v[68:71], v[166:169], v[212:215], v[68:71]
	v_mfma_f32_16x16x32_bf16 v[64:67], v[174:177], v[212:215], v[64:67]
	s_barrier
	s_setprio 0
	s_add_i32 s38, s38, s41
	v_lshl_add_u64 v[160:161], s[30:31], 0, v[146:147]
	s_mov_b32 m0, s38
	ds_read_b128 v[178:181], v164 offset:16384
	ds_read_b128 v[182:185], v164 offset:17408
	ds_read_b128 v[186:189], v164 offset:18432
	ds_read_b128 v[190:193], v164 offset:19456
	ds_read_b128 v[200:203], v164 offset:20480
	ds_read_b128 v[204:207], v164 offset:21504
	ds_read_b128 v[208:211], v164 offset:22528
	ds_read_b128 v[212:215], v164 offset:23552
	global_load_lds_dwordx4 v[160:161], off
	s_add_i32 m0, s38, 0x2000
	s_add_u32 s38, s30, 0x20000
	v_lshl_add_u64 v[216:217], s[30:31], 0, v[150:151]
	s_addc_u32 s39, s31, 0
	s_add_i32 s59, s59, s41
	global_load_lds_dwordx4 v[216:217], off
	v_lshl_add_u64 v[218:219], s[38:39], 0, v[146:147]
	s_mov_b32 m0, s59
	v_lshl_add_u64 v[220:221], s[34:35], 0, v[148:149]
	global_load_lds_dwordx4 v[218:219], off
	v_lshl_add_u64 v[218:219], s[38:39], 0, v[150:151]
	s_add_i32 m0, s59, 0x2000
	s_nop 0
	global_load_lds_dwordx4 v[218:219], off
	v_lshl_add_u64 v[218:219], s[34:35], 0, v[144:145]
	s_mov_b32 m0, s42
	s_nop 0
	global_load_lds_dwordx4 v[218:219], off
	s_mov_b32 m0, s43
	s_nop 0
	global_load_lds_dwordx4 v[220:221], off
	s_waitcnt vmcnt(8)
	s_waitcnt lgkmcnt(0)
	s_setprio 1
	s_barrier
; #define PG8_STAGE(bufoff, gbase, voff) do { _Pragma("unroll") for (int _i = 0; _i < 2; ++_i) \
;         __builtin_amdgcn_global_load_lds((const unsigned*)((const char*)(gbase) + (voff)[_i]), (LAS unsigned*)(lds + (bufoff) + ldsw + _i * 8192), 16, 0, 0); } while (0)
; #define PG8_LDA(dst, b, h) do { _Pragma("unroll") for (int m = 0; m < 4; ++m) _Pragma("unroll") for (int k = 0; k < 2; ++k) dst[m][k] = *(const LAS bf16x8*)(lds + PG8_SA(b, h) + aoff + m * 2048 + k * 1024); } while (0)
; #define PG8_LDB(dst, b, h) do { _Pragma("unroll") for (int n = 0; n < 2; ++n) _Pragma("unroll") for (int k = 0; k < 2; ++k) dst[n][k] = *(const LAS bf16x8*)(lds + PG8_SB(b, h) + boff + n * 2048 + k * 1024); } while (0)
; #define PG8_MMA(ai, bj, At, Bt) do { __builtin_amdgcn_s_setprio(1); _Pragma("unroll") for (int m = 0; m < 4; ++m) _Pragma("unroll") for (int n = 0; n < 2; ++n) _Pragma("unroll") for (int k = 0; k < 2; ++k) \
;         acc[ai][bj][m][n] = __builtin_amdgcn_mfma_f32_16x16x32_bf16(Bt[n][k], At[m][k], acc[ai][bj][m][n], 0, 0, 0); __builtin_amdgcn_s_setprio(0); } while (0)
; #define PG8_WAIT_V(n) asm volatile("s_waitcnt vmcnt(" #n ")" ::: "memory")
; #define PG8_WAIT_L(n) asm volatile("s_waitcnt lgkmcnt(" #n ")" ::: "memory")
; #define PG8_BAR __builtin_amdgcn_s_barrier()
; #define PG8_SCHED __builtin_amdgcn_sched_barrier(0)
; template <class Epi, class Sched>
; __device__ __forceinline__ void gemm_stream(LAS unsigned char* lds, const int lda, const int ldb, const Sched& S, const Epi& E, const int wv) {
;     ...
;             PG8_WAIT_V(8); PG8_WAIT_L(0); PG8_BAR; PG8_MMA(1, 0, At, B0); PG8_MMA(1, 1, At, B1); PG8_BAR; PG8_SCHED;
;             PG8_LDB(B0, 1, 0); PG8_LDB(B1, 1, 1); PG8_SCHED; PG8_LDA(At, 1, 0); PG8_STAGE(PG8_SA(0, 1), a2 + hstepA, voffA);
;             PG8_WAIT_V(8); PG8_WAIT_L(0); PG8_BAR; PG8_MMA(0, 0, At, B0); PG8_MMA(0, 1, At, B1); PG8_BAR; PG8_SCHED;
;             PG8_LDA(At, 1, 1); PG8_STAGE(PG8_SB(1, 0), b3, voffB); PG8_STAGE(PG8_SB(1, 1), b3 + hstepB, voffB); PG8_STAGE(PG8_SA(1, 0), a3, voffA);
;             PG8_WAIT_V(8); PG8_WAIT_L(0); PG8_BAR; PG8_MMA(1, 0, At, B0); PG8_MMA(1, 1, At, B1); PG8_BAR; PG8_SCHED;
	v_mfma_f32_16x16x32_bf16 v[60:63], v[128:131], v[178:181], v[60:63]
	v_mfma_f32_16x16x32_bf16 v[56:59], v[136:139], v[178:181], v[56:59]
	v_mfma_f32_16x16x32_bf16 v[44:47], v[128:131], v[186:189], v[44:47]
	v_mfma_f32_16x16x32_bf16 v[40:43], v[136:139], v[186:189], v[40:43]
	v_mfma_f32_16x16x32_bf16 v[28:31], v[128:131], v[200:203], v[28:31]
	v_mfma_f32_16x16x32_bf16 v[24:27], v[136:139], v[200:203], v[24:27]
	v_mfma_f32_16x16x32_bf16 v[12:15], v[128:131], v[208:211], v[12:15]
	v_mfma_f32_16x16x32_bf16 v[8:11], v[136:139], v[208:211], v[8:11]
	v_mfma_f32_16x16x32_bf16 v[60:63], v[132:135], v[182:185], v[60:63]
	v_mfma_f32_16x16x32_bf16 v[56:59], v[140:143], v[182:185], v[56:59]
	v_mfma_f32_16x16x32_bf16 v[44:47], v[132:135], v[190:193], v[44:47]
	v_mfma_f32_16x16x32_bf16 v[40:43], v[140:143], v[190:193], v[40:43]
	v_mfma_f32_16x16x32_bf16 v[28:31], v[132:135], v[204:207], v[28:31]
	v_mfma_f32_16x16x32_bf16 v[24:27], v[140:143], v[204:207], v[24:27]
	v_mfma_f32_16x16x32_bf16 v[12:15], v[132:135], v[212:215], v[12:15]
	v_mfma_f32_16x16x32_bf16 v[8:11], v[140:143], v[212:215], v[8:11]
	v_mfma_f32_16x16x32_bf16 v[52:55], v[156:159], v[178:181], v[52:55]
	v_mfma_f32_16x16x32_bf16 v[48:51], v[170:173], v[178:181], v[48:51]
	v_mfma_f32_16x16x32_bf16 v[36:39], v[156:159], v[186:189], v[36:39]
	v_mfma_f32_16x16x32_bf16 v[32:35], v[170:173], v[186:189], v[32:35]
	v_mfma_f32_16x16x32_bf16 v[20:23], v[156:159], v[200:203], v[20:23]
	v_mfma_f32_16x16x32_bf16 v[16:19], v[170:173], v[200:203], v[16:19]
	v_mfma_f32_16x16x32_bf16 v[4:7], v[156:159], v[208:211], v[4:7]
	v_mfma_f32_16x16x32_bf16 v[0:3], v[170:173], v[208:211], v[0:3]
	v_mfma_f32_16x16x32_bf16 v[52:55], v[166:169], v[182:185], v[52:55]
	v_mfma_f32_16x16x32_bf16 v[48:51], v[174:177], v[182:185], v[48:51]
	v_mfma_f32_16x16x32_bf16 v[36:39], v[166:169], v[190:193], v[36:39]
	v_mfma_f32_16x16x32_bf16 v[32:35], v[174:177], v[190:193], v[32:35]
	v_mfma_f32_16x16x32_bf16 v[20:23], v[166:169], v[204:207], v[20:23]
	v_mfma_f32_16x16x32_bf16 v[16:19], v[174:177], v[204:207], v[16:19]
	v_mfma_f32_16x16x32_bf16 v[4:7], v[166:169], v[212:215], v[4:7]
	v_mfma_f32_16x16x32_bf16 v[0:3], v[174:177], v[212:215], v[0:3]
	s_barrier
	s_setprio 0
	s_add_i32 s38, 0, 0x18000
	s_add_i32 s39, 0, 0x1c000
	v_add_u32_e32 v140, s38, v163
	v_add_u32_e32 v165, s39, v163
	ds_read_b128 v[128:131], v140
	ds_read_b128 v[132:135], v140 offset:1024
	ds_read_b128 v[136:139], v140 offset:2048
	ds_read_b128 v[140:143], v140 offset:3072
	ds_read_b128 v[156:159], v165
	ds_read_b128 v[166:169], v165 offset:1024
	ds_read_b128 v[170:173], v165 offset:2048
	ds_read_b128 v[174:177], v165 offset:3072
	s_add_u32 s34, s34, 0x80000
	s_addc_u32 s35, s35, 0
	s_mov_b32 m0, s44
	v_lshl_add_u64 v[222:223], s[34:35], 0, v[144:145]
	ds_read_b128 v[178:181], v164 offset:32768
	ds_read_b128 v[182:185], v164 offset:33792
	ds_read_b128 v[186:189], v164 offset:34816
	ds_read_b128 v[190:193], v164 offset:35840
	ds_read_b128 v[200:203], v164 offset:36864
	ds_read_b128 v[204:207], v164 offset:37888
	ds_read_b128 v[208:211], v164 offset:38912
	ds_read_b128 v[212:215], v164 offset:39936
	global_load_lds_dwordx4 v[222:223], off
	v_lshl_add_u64 v[222:223], s[34:35], 0, v[148:149]
	s_mov_b32 m0, s45
	s_nop 0
	global_load_lds_dwordx4 v[222:223], off
	s_waitcnt vmcnt(8)
	s_waitcnt lgkmcnt(0)
	s_setprio 1
	s_barrier
	v_mfma_f32_16x16x32_bf16 v[124:127], v[128:131], v[178:181], v[124:127]
	v_mfma_f32_16x16x32_bf16 v[120:123], v[136:139], v[178:181], v[120:123]
	v_mfma_f32_16x16x32_bf16 v[108:111], v[128:131], v[186:189], v[108:111]
	v_mfma_f32_16x16x32_bf16 v[104:107], v[136:139], v[186:189], v[104:107]
	v_mfma_f32_16x16x32_bf16 v[92:95], v[128:131], v[200:203], v[92:95]
	v_mfma_f32_16x16x32_bf16 v[88:91], v[136:139], v[200:203], v[88:91]
	v_mfma_f32_16x16x32_bf16 v[76:79], v[128:131], v[208:211], v[76:79]
	v_mfma_f32_16x16x32_bf16 v[72:75], v[136:139], v[208:211], v[72:75]
	v_mfma_f32_16x16x32_bf16 v[124:127], v[132:135], v[182:185], v[124:127]
	v_mfma_f32_16x16x32_bf16 v[120:123], v[140:143], v[182:185], v[120:123]
	v_mfma_f32_16x16x32_bf16 v[108:111], v[132:135], v[190:193], v[108:111]
	v_mfma_f32_16x16x32_bf16 v[104:107], v[140:143], v[190:193], v[104:107]
	v_mfma_f32_16x16x32_bf16 v[92:95], v[132:135], v[204:207], v[92:95]
	v_mfma_f32_16x16x32_bf16 v[88:91], v[140:143], v[204:207], v[88:91]
	v_mfma_f32_16x16x32_bf16 v[76:79], v[132:135], v[212:215], v[76:79]
	v_mfma_f32_16x16x32_bf16 v[72:75], v[140:143], v[212:215], v[72:75]
	v_mfma_f32_16x16x32_bf16 v[116:119], v[156:159], v[178:181], v[116:119]
	v_mfma_f32_16x16x32_bf16 v[112:115], v[170:173], v[178:181], v[112:115]
	v_mfma_f32_16x16x32_bf16 v[100:103], v[156:159], v[186:189], v[100:103]
	v_mfma_f32_16x16x32_bf16 v[96:99], v[170:173], v[186:189], v[96:99]
	v_mfma_f32_16x16x32_bf16 v[84:87], v[156:159], v[200:203], v[84:87]
	v_mfma_f32_16x16x32_bf16 v[80:83], v[170:173], v[200:203], v[80:83]
	v_mfma_f32_16x16x32_bf16 v[68:71], v[156:159], v[208:211], v[68:71]
	v_mfma_f32_16x16x32_bf16 v[64:67], v[170:173], v[208:211], v[64:67]
	v_mfma_f32_16x16x32_bf16 v[116:119], v[166:169], v[182:185], v[116:119]
	v_mfma_f32_16x16x32_bf16 v[112:115], v[174:177], v[182:185], v[112:115]
	v_mfma_f32_16x16x32_bf16 v[100:103], v[166:169], v[190:193], v[100:103]
	v_mfma_f32_16x16x32_bf16 v[96:99], v[174:177], v[190:193], v[96:99]
	v_mfma_f32_16x16x32_bf16 v[84:87], v[166:169], v[204:207], v[84:87]
	v_mfma_f32_16x16x32_bf16 v[80:83], v[174:177], v[204:207], v[80:83]
	v_mfma_f32_16x16x32_bf16 v[68:71], v[166:169], v[212:215], v[68:71]
	v_mfma_f32_16x16x32_bf16 v[64:67], v[174:177], v[212:215], v[64:67]
	s_barrier
; #define PG8_STAGE(bufoff, gbase, voff) do { _Pragma("unroll") for (int _i = 0; _i < 2; ++_i) \
;         __builtin_amdgcn_global_load_lds((const unsigned*)((const char*)(gbase) + (voff)[_i]), (LAS unsigned*)(lds + (bufoff) + ldsw + _i * 8192), 16, 0, 0); } while (0)
; #define PG8_LDA(dst, b, h) do { _Pragma("unroll") for (int m = 0; m < 4; ++m) _Pragma("unroll") for (int k = 0; k < 2; ++k) dst[m][k] = *(const LAS bf16x8*)(lds + PG8_SA(b, h) + aoff + m * 2048 + k * 1024); } while (0)
; #define PG8_MMA(ai, bj, At, Bt) do { __builtin_amdgcn_s_setprio(1); _Pragma("unroll") for (int m = 0; m < 4; ++m) _Pragma("unroll") for (int n = 0; n < 2; ++n) _Pragma("unroll") for (int k = 0; k < 2; ++k) \
;         acc[ai][bj][m][n] = __builtin_amdgcn_mfma_f32_16x16x32_bf16(Bt[n][k], At[m][k], acc[ai][bj][m][n], 0, 0, 0); __builtin_amdgcn_s_setprio(0); } while (0)
; #define PG8_WAIT_V(n) asm volatile("s_waitcnt vmcnt(" #n ")" ::: "memory")
; #define PG8_WAIT_L(n) asm volatile("s_waitcnt lgkmcnt(" #n ")" ::: "memory")
; #define PG8_BAR __builtin_amdgcn_s_barrier()
; #define PG8_SCHED __builtin_amdgcn_sched_barrier(0)
; template <class Epi, class Sched>
; __device__ __forceinline__ void gemm_stream(LAS unsigned char* lds, const int lda, const int ldb, const Sched& S, const Epi& E, const int wv) {
;     ...
;             PG8_LDA(At, 1, 1); PG8_STAGE(PG8_SB(1, 0), b3, voffB); PG8_STAGE(PG8_SB(1, 1), b3 + hstepB, voffB); PG8_STAGE(PG8_SA(1, 0), a3, voffA);
;             PG8_WAIT_V(8); PG8_WAIT_L(0); PG8_BAR; PG8_MMA(1, 0, At, B0); PG8_MMA(1, 1, At, B1); PG8_BAR; PG8_SCHED;
;         }
	s_setprio 0
	s_add_i32 s34, s38, s41
	v_lshl_add_u64 v[160:161], v[160:161], 0, s[78:79]
	s_mov_b32 m0, s34
	ds_read_b128 v[178:181], v164 offset:49152
	ds_read_b128 v[182:185], v164 offset:50176
	ds_read_b128 v[186:189], v164 offset:51200
	ds_read_b128 v[190:193], v164 offset:52224
	ds_read_b128 v[200:203], v164 offset:53248
	ds_read_b128 v[204:207], v164 offset:54272
	ds_read_b128 v[208:211], v164 offset:55296
	ds_read_b128 v[212:215], v164 offset:56320
	global_load_lds_dwordx4 v[160:161], off
	s_add_i32 m0, s34, 0x2000
	s_add_u32 s30, s30, 0x20080
	v_lshl_add_u64 v[160:161], v[216:217], 0, s[78:79]
	s_addc_u32 s31, s31, 0
	s_add_i32 s34, s39, s41
	global_load_lds_dwordx4 v[160:161], off
	v_lshl_add_u64 v[160:161], s[30:31], 0, v[146:147]
	s_mov_b32 m0, s34
	s_nop 0
	global_load_lds_dwordx4 v[160:161], off
	v_lshl_add_u64 v[160:161], s[30:31], 0, v[150:151]
	s_add_i32 m0, s34, 0x2000
	s_nop 0
	global_load_lds_dwordx4 v[160:161], off
	v_lshl_add_u64 v[160:161], v[218:219], 0, s[78:79]
	s_mov_b32 m0, s49
	s_nop 0
	global_load_lds_dwordx4 v[160:161], off
	v_lshl_add_u64 v[160:161], v[220:221], 0, s[78:79]
	s_mov_b32 m0, s50
	s_nop 0
	global_load_lds_dwordx4 v[160:161], off
	s_waitcnt vmcnt(8)
	s_waitcnt lgkmcnt(0)
	s_setprio 1
	s_barrier
	v_mfma_f32_16x16x32_bf16 v[60:63], v[128:131], v[178:181], v[60:63]
	v_mfma_f32_16x16x32_bf16 v[56:59], v[136:139], v[178:181], v[56:59]
	v_mfma_f32_16x16x32_bf16 v[44:47], v[128:131], v[186:189], v[44:47]
	v_mfma_f32_16x16x32_bf16 v[40:43], v[136:139], v[186:189], v[40:43]
	v_mfma_f32_16x16x32_bf16 v[28:31], v[128:131], v[200:203], v[28:31]
	v_mfma_f32_16x16x32_bf16 v[24:27], v[136:139], v[200:203], v[24:27]
	v_mfma_f32_16x16x32_bf16 v[12:15], v[128:131], v[208:211], v[12:15]
	v_mfma_f32_16x16x32_bf16 v[8:11], v[136:139], v[208:211], v[8:11]
	v_mfma_f32_16x16x32_bf16 v[60:63], v[132:135], v[182:185], v[60:63]
	v_mfma_f32_16x16x32_bf16 v[56:59], v[140:143], v[182:185], v[56:59]
	v_mfma_f32_16x16x32_bf16 v[44:47], v[132:135], v[190:193], v[44:47]
	v_mfma_f32_16x16x32_bf16 v[40:43], v[140:143], v[190:193], v[40:43]
	v_mfma_f32_16x16x32_bf16 v[28:31], v[132:135], v[204:207], v[28:31]
	v_mfma_f32_16x16x32_bf16 v[24:27], v[140:143], v[204:207], v[24:27]
	v_mfma_f32_16x16x32_bf16 v[12:15], v[132:135], v[212:215], v[12:15]
	v_mfma_f32_16x16x32_bf16 v[8:11], v[140:143], v[212:215], v[8:11]
	v_mfma_f32_16x16x32_bf16 v[52:55], v[156:159], v[178:181], v[52:55]
	v_mfma_f32_16x16x32_bf16 v[48:51], v[170:173], v[178:181], v[48:51]
	v_mfma_f32_16x16x32_bf16 v[36:39], v[156:159], v[186:189], v[36:39]
	v_mfma_f32_16x16x32_bf16 v[32:35], v[170:173], v[186:189], v[32:35]
	v_mfma_f32_16x16x32_bf16 v[20:23], v[156:159], v[200:203], v[20:23]
	v_mfma_f32_16x16x32_bf16 v[16:19], v[170:173], v[200:203], v[16:19]
	v_mfma_f32_16x16x32_bf16 v[4:7], v[156:159], v[208:211], v[4:7]
	v_mfma_f32_16x16x32_bf16 v[0:3], v[170:173], v[208:211], v[0:3]
	v_mfma_f32_16x16x32_bf16 v[52:55], v[166:169], v[182:185], v[52:55]
	v_mfma_f32_16x16x32_bf16 v[48:51], v[174:177], v[182:185], v[48:51]
	v_mfma_f32_16x16x32_bf16 v[36:39], v[166:169], v[190:193], v[36:39]
	v_mfma_f32_16x16x32_bf16 v[32:35], v[174:177], v[190:193], v[32:35]
	v_mfma_f32_16x16x32_bf16 v[20:23], v[166:169], v[204:207], v[20:23]
	v_mfma_f32_16x16x32_bf16 v[16:19], v[174:177], v[204:207], v[16:19]
	v_mfma_f32_16x16x32_bf16 v[4:7], v[166:169], v[212:215], v[4:7]
	v_mfma_f32_16x16x32_bf16 v[0:3], v[174:177], v[212:215], v[0:3]
	s_barrier
	s_setprio 0
	s_add_i32 s37, s37, 2
	s_add_u32 s28, s28, 0x100
	s_addc_u32 s29, s29, 0
	s_add_u32 s33, s33, 0x100
	s_addc_u32 s36, s36, 0
	s_cmp_gt_u32 s37, 29
	s_cbranch_scc0 .LBB0_222
	s_and_b64 vcc, exec, s[14:15]
	s_cbranch_vccz .LBB0_225
	s_barrier

; #define PG8_STAGE(bufoff, gbase, voff) do { _Pragma("unroll") for (int _i = 0; _i < 2; ++_i) \
;         __builtin_amdgcn_global_load_lds((const unsigned*)((const char*)(gbase) + (voff)[_i]), (LAS unsigned*)(lds + (bufoff) + ldsw + _i * 8192), 16, 0, 0); } while (0)
; #define PG8_LDA(dst, b, h) do { _Pragma("unroll") for (int m = 0; m < 4; ++m) _Pragma("unroll") for (int k = 0; k < 2; ++k) dst[m][k] = *(const LAS bf16x8*)(lds + PG8_SA(b, h) + aoff + m * 2048 + k * 1024); } while (0)
; #define PG8_LDB(dst, b, h) do { _Pragma("unroll") for (int n = 0; n < 2; ++n) _Pragma("unroll") for (int k = 0; k < 2; ++k) dst[n][k] = *(const LAS bf16x8*)(lds + PG8_SB(b, h) + boff + n * 2048 + k * 1024); } while (0)
; #define PG8_MMA(ai, bj, At, Bt) do { __builtin_amdgcn_s_setprio(1); _Pragma("unroll") for (int m = 0; m < 4; ++m) _Pragma("unroll") for (int n = 0; n < 2; ++n) _Pragma("unroll") for (int k = 0; k < 2; ++k) \
;         acc[ai][bj][m][n] = __builtin_amdgcn_mfma_f32_16x16x32_bf16(Bt[n][k], At[m][k], acc[ai][bj][m][n], 0, 0, 0); __builtin_amdgcn_s_setprio(0); } while (0)
; #define PG8_WAIT_V(n) asm volatile("s_waitcnt vmcnt(" #n ")" ::: "memory")
; #define PG8_WAIT_L(n) asm volatile("s_waitcnt lgkmcnt(" #n ")" ::: "memory")
; #define PG8_BAR __builtin_amdgcn_s_barrier()
; #define PG8_SCHED __builtin_amdgcn_sched_barrier(0)
; template <class Epi, class Sched>
; __device__ __forceinline__ void gemm_stream(LAS unsigned char* lds, const int lda, const int ldb, const Sched& S, const Epi& E, const int wv) {
;     ...
;         for (int t = 0; t < nt; t += 2) {
;             const bool last = (t == nt - 2);
;             const char* a1 = cA + (size_t)(t + 1) * kstep;
;             const char* a2 = last ? nA : cA + (size_t)(t + 2) * kstep; const char* b2 = last ? nB : cB + (size_t)(t + 2) * kstep;
;             const char* a3 = a2 + kstep; const char* b3 = b2 + kstep;
;             PG8_LDB(B0, 0, 0); PG8_LDB(B1, 0, 1); PG8_SCHED; PG8_LDA(At, 0, 0); PG8_STAGE(PG8_SA(1, 1), a1 + hstepA, voffA);
;             PG8_WAIT_V(8); PG8_WAIT_L(0); PG8_BAR; PG8_MMA(0, 0, At, B0); PG8_MMA(0, 1, At, B1); PG8_BAR; PG8_SCHED;
;             PG8_LDA(At, 0, 1); PG8_STAGE(PG8_SB(0, 0), b2, voffB); PG8_STAGE(PG8_SB(0, 1), b2 + hstepB, voffB); PG8_STAGE(PG8_SA(0, 0), a2, voffA);
;             PG8_WAIT_V(8); PG8_WAIT_L(0); PG8_BAR; PG8_MMA(1, 0, At, B0); PG8_MMA(1, 1, At, B1); PG8_BAR; PG8_SCHED;
.LBB0_496:
	s_add_i32 s63, s24, 2
	s_add_u32 s22, s4, 0x100
	s_addc_u32 s23, s5, 0
	s_add_i32 s66, 0, 0x10000
	s_cmp_eq_u32 s60, s24
	s_cselect_b32 s27, s33, s23
	s_cselect_b32 s26, s57, s22
	v_add_u32_e32 v120, s66, v235
	s_cselect_b32 s25, s58, s62
	s_cselect_b32 s24, s59, s61
	s_add_i32 s67, 0, 0x14000
	ds_read_b128 v[130:133], v120
	ds_read_b128 v[134:137], v120 offset:1024
	ds_read_b128 v[138:141], v120 offset:2048
	ds_read_b128 v[142:145], v120 offset:3072
	v_add_u32_e32 v120, s67, v235
	ds_read_b128 v[146:149], v120
	ds_read_b128 v[150:153], v120 offset:1024
	ds_read_b128 v[154:157], v120 offset:2048
	ds_read_b128 v[158:161], v120 offset:3072
	v_lshl_add_u64 v[120:121], s[4:5], 0, v[208:209]
	s_add_i32 m0, s36, 0xc000
	ds_read_b128 v[162:165], v236
	ds_read_b128 v[166:169], v236 offset:1024
	ds_read_b128 v[170:173], v236 offset:2048
	ds_read_b128 v[174:177], v236 offset:3072
	ds_read_b128 v[178:181], v236 offset:4096
	ds_read_b128 v[182:185], v236 offset:5120
	ds_read_b128 v[186:189], v236 offset:6144
	ds_read_b128 v[190:193], v236 offset:7168
	global_load_lds_dwordx4 v[120:121], off
	v_lshl_add_u64 v[120:121], s[4:5], 0, v[210:211]
	s_add_i32 m0, s36, 0xe000
	s_nop 0
	global_load_lds_dwordx4 v[120:121], off
	s_waitcnt vmcnt(8)
	s_waitcnt lgkmcnt(0)
	s_setprio 1
	s_barrier
	v_mfma_f32_16x16x32_bf16 v[126:129], v[130:133], v[162:165], v[126:129]
	v_mfma_f32_16x16x32_bf16 v[120:123], v[138:141], v[162:165], v[122:125]
	v_mfma_f32_16x16x32_bf16 v[116:119], v[130:133], v[170:173], v[116:119]
	v_mfma_f32_16x16x32_bf16 v[112:115], v[138:141], v[170:173], v[112:115]
	v_mfma_f32_16x16x32_bf16 v[100:103], v[130:133], v[178:181], v[100:103]
	v_mfma_f32_16x16x32_bf16 v[96:99], v[138:141], v[178:181], v[96:99]
	v_mfma_f32_16x16x32_bf16 v[84:87], v[130:133], v[186:189], v[84:87]
	v_mfma_f32_16x16x32_bf16 v[80:83], v[138:141], v[186:189], v[80:83]
	v_mfma_f32_16x16x32_bf16 v[126:129], v[134:137], v[166:169], v[126:129]
	v_mfma_f32_16x16x32_bf16 v[120:123], v[142:145], v[166:169], v[120:123]
	v_mfma_f32_16x16x32_bf16 v[116:119], v[134:137], v[174:177], v[116:119]
	v_mfma_f32_16x16x32_bf16 v[112:115], v[142:145], v[174:177], v[112:115]
	v_mfma_f32_16x16x32_bf16 v[100:103], v[134:137], v[182:185], v[100:103]
	v_mfma_f32_16x16x32_bf16 v[96:99], v[142:145], v[182:185], v[96:99]
	v_mfma_f32_16x16x32_bf16 v[84:87], v[134:137], v[190:193], v[84:87]
	v_mfma_f32_16x16x32_bf16 v[80:83], v[142:145], v[190:193], v[80:83]
	v_mfma_f32_16x16x32_bf16 v[108:111], v[146:149], v[162:165], v[108:111]
	v_mfma_f32_16x16x32_bf16 v[104:107], v[154:157], v[162:165], v[104:107]
	v_mfma_f32_16x16x32_bf16 v[92:95], v[146:149], v[170:173], v[92:95]
	v_mfma_f32_16x16x32_bf16 v[88:91], v[154:157], v[170:173], v[88:91]
	v_mfma_f32_16x16x32_bf16 v[76:79], v[146:149], v[178:181], v[76:79]
	v_mfma_f32_16x16x32_bf16 v[72:75], v[154:157], v[178:181], v[72:75]
	v_mfma_f32_16x16x32_bf16 v[68:71], v[146:149], v[186:189], v[68:71]
	v_mfma_f32_16x16x32_bf16 v[64:67], v[154:157], v[186:189], v[64:67]
	v_mfma_f32_16x16x32_bf16 v[108:111], v[150:153], v[166:169], v[108:111]
	v_mfma_f32_16x16x32_bf16 v[104:107], v[158:161], v[166:169], v[104:107]
	v_mfma_f32_16x16x32_bf16 v[92:95], v[150:153], v[174:177], v[92:95]
	v_mfma_f32_16x16x32_bf16 v[88:91], v[158:161], v[174:177], v[88:91]
	v_mfma_f32_16x16x32_bf16 v[76:79], v[150:153], v[182:185], v[76:79]
	v_mfma_f32_16x16x32_bf16 v[72:75], v[158:161], v[182:185], v[72:75]
	v_mfma_f32_16x16x32_bf16 v[68:71], v[150:153], v[190:193], v[68:71]
	v_mfma_f32_16x16x32_bf16 v[64:67], v[158:161], v[190:193], v[64:67]
	s_barrier
	s_setprio 0
	s_add_i32 s4, s66, s35
	v_lshl_add_u64 v[196:197], s[24:25], 0, v[202:203]
	s_mov_b32 m0, s4
	ds_read_b128 v[162:165], v236 offset:16384
	ds_read_b128 v[166:169], v236 offset:17408
	ds_read_b128 v[170:173], v236 offset:18432
	ds_read_b128 v[174:177], v236 offset:19456
	ds_read_b128 v[178:181], v236 offset:20480
	ds_read_b128 v[182:185], v236 offset:21504
	ds_read_b128 v[186:189], v236 offset:22528
	ds_read_b128 v[190:193], v236 offset:23552
	global_load_lds_dwordx4 v[196:197], off
	s_add_i32 m0, s4, 0x2000
	s_add_u32 s4, s24, 0x20000
	v_lshl_add_u64 v[198:199], s[24:25], 0, v[206:207]
	s_addc_u32 s5, s25, 0
	s_add_i32 s66, s67, s35
	global_load_lds_dwordx4 v[198:199], off
	v_lshl_add_u64 v[124:125], s[4:5], 0, v[202:203]
	s_mov_b32 m0, s66
	v_lshl_add_u64 v[212:213], s[26:27], 0, v[200:201]
	global_load_lds_dwordx4 v[124:125], off
	v_lshl_add_u64 v[124:125], s[4:5], 0, v[206:207]
	s_add_i32 m0, s66, 0x2000
	v_lshl_add_u64 v[214:215], s[26:27], 0, v[204:205]
	global_load_lds_dwordx4 v[124:125], off
	s_mov_b32 m0, s36
	s_nop 0
	global_load_lds_dwordx4 v[212:213], off
	s_mov_b32 m0, s37
	s_nop 0
	global_load_lds_dwordx4 v[214:215], off
	s_waitcnt vmcnt(8)
	s_waitcnt lgkmcnt(0)
	s_setprio 1
	s_barrier
; #define PG8_STAGE(bufoff, gbase, voff) do { _Pragma("unroll") for (int _i = 0; _i < 2; ++_i) \
;         __builtin_amdgcn_global_load_lds((const unsigned*)((const char*)(gbase) + (voff)[_i]), (LAS unsigned*)(lds + (bufoff) + ldsw + _i * 8192), 16, 0, 0); } while (0)
; #define PG8_LDA(dst, b, h) do { _Pragma("unroll") for (int m = 0; m < 4; ++m) _Pragma("unroll") for (int k = 0; k < 2; ++k) dst[m][k] = *(const LAS bf16x8*)(lds + PG8_SA(b, h) + aoff + m * 2048 + k * 1024); } while (0)
; #define PG8_LDB(dst, b, h) do { _Pragma("unroll") for (int n = 0; n < 2; ++n) _Pragma("unroll") for (int k = 0; k < 2; ++k) dst[n][k] = *(const LAS bf16x8*)(lds + PG8_SB(b, h) + boff + n * 2048 + k * 1024); } while (0)
; #define PG8_MMA(ai, bj, At, Bt) do { __builtin_amdgcn_s_setprio(1); _Pragma("unroll") for (int m = 0; m < 4; ++m) _Pragma("unroll") for (int n = 0; n < 2; ++n) _Pragma("unroll") for (int k = 0; k < 2; ++k) \
;         acc[ai][bj][m][n] = __builtin_amdgcn_mfma_f32_16x16x32_bf16(Bt[n][k], At[m][k], acc[ai][bj][m][n], 0, 0, 0); __builtin_amdgcn_s_setprio(0); } while (0)
; #define PG8_WAIT_V(n) asm volatile("s_waitcnt vmcnt(" #n ")" ::: "memory")
; #define PG8_WAIT_L(n) asm volatile("s_waitcnt lgkmcnt(" #n ")" ::: "memory")
; #define PG8_BAR __builtin_amdgcn_s_barrier()
; #define PG8_SCHED __builtin_amdgcn_sched_barrier(0)
; template <class Epi, class Sched>
; __device__ __forceinline__ void gemm_stream(LAS unsigned char* lds, const int lda, const int ldb, const Sched& S, const Epi& E, const int wv) {
;     ...
;             PG8_WAIT_V(8); PG8_WAIT_L(0); PG8_BAR; PG8_MMA(1, 0, At, B0); PG8_MMA(1, 1, At, B1); PG8_BAR; PG8_SCHED;
;             PG8_LDB(B0, 1, 0); PG8_LDB(B1, 1, 1); PG8_SCHED; PG8_LDA(At, 1, 0); PG8_STAGE(PG8_SA(0, 1), a2 + hstepA, voffA);
;             PG8_WAIT_V(8); PG8_WAIT_L(0); PG8_BAR; PG8_MMA(0, 0, At, B0); PG8_MMA(0, 1, At, B1); PG8_BAR; PG8_SCHED;
;             PG8_LDA(At, 1, 1); PG8_STAGE(PG8_SB(1, 0), b3, voffB); PG8_STAGE(PG8_SB(1, 1), b3 + hstepB, voffB); PG8_STAGE(PG8_SA(1, 0), a3, voffA);
;             PG8_WAIT_V(8); PG8_WAIT_L(0); PG8_BAR; PG8_MMA(1, 0, At, B0); PG8_MMA(1, 1, At, B1); PG8_BAR; PG8_SCHED;
	v_mfma_f32_16x16x32_bf16 v[60:63], v[130:133], v[162:165], v[60:63]
	v_mfma_f32_16x16x32_bf16 v[56:59], v[138:141], v[162:165], v[56:59]
	v_mfma_f32_16x16x32_bf16 v[52:55], v[130:133], v[170:173], v[52:55]
	v_mfma_f32_16x16x32_bf16 v[48:51], v[138:141], v[170:173], v[48:51]
	v_mfma_f32_16x16x32_bf16 v[36:39], v[130:133], v[178:181], v[36:39]
	v_mfma_f32_16x16x32_bf16 v[32:35], v[138:141], v[178:181], v[32:35]
	v_mfma_f32_16x16x32_bf16 v[20:23], v[130:133], v[186:189], v[20:23]
	v_mfma_f32_16x16x32_bf16 v[16:19], v[138:141], v[186:189], v[16:19]
	v_mfma_f32_16x16x32_bf16 v[60:63], v[134:137], v[166:169], v[60:63]
	v_mfma_f32_16x16x32_bf16 v[56:59], v[142:145], v[166:169], v[56:59]
	v_mfma_f32_16x16x32_bf16 v[52:55], v[134:137], v[174:177], v[52:55]
	v_mfma_f32_16x16x32_bf16 v[48:51], v[142:145], v[174:177], v[48:51]
	v_mfma_f32_16x16x32_bf16 v[36:39], v[134:137], v[182:185], v[36:39]
	v_mfma_f32_16x16x32_bf16 v[32:35], v[142:145], v[182:185], v[32:35]
	v_mfma_f32_16x16x32_bf16 v[20:23], v[134:137], v[190:193], v[20:23]
	v_mfma_f32_16x16x32_bf16 v[16:19], v[142:145], v[190:193], v[16:19]
	v_mfma_f32_16x16x32_bf16 v[44:47], v[146:149], v[162:165], v[44:47]
	v_mfma_f32_16x16x32_bf16 v[40:43], v[154:157], v[162:165], v[40:43]
	v_mfma_f32_16x16x32_bf16 v[28:31], v[146:149], v[170:173], v[28:31]
	v_mfma_f32_16x16x32_bf16 v[24:27], v[154:157], v[170:173], v[24:27]
	v_mfma_f32_16x16x32_bf16 v[12:15], v[146:149], v[178:181], v[12:15]
	v_mfma_f32_16x16x32_bf16 v[8:11], v[154:157], v[178:181], v[8:11]
	v_mfma_f32_16x16x32_bf16 v[4:7], v[146:149], v[186:189], v[4:7]
	v_mfma_f32_16x16x32_bf16 v[0:3], v[154:157], v[186:189], v[0:3]
	v_mfma_f32_16x16x32_bf16 v[44:47], v[150:153], v[166:169], v[44:47]
	v_mfma_f32_16x16x32_bf16 v[40:43], v[158:161], v[166:169], v[40:43]
	v_mfma_f32_16x16x32_bf16 v[28:31], v[150:153], v[174:177], v[28:31]
	v_mfma_f32_16x16x32_bf16 v[24:27], v[158:161], v[174:177], v[24:27]
	v_mfma_f32_16x16x32_bf16 v[12:15], v[150:153], v[182:185], v[12:15]
	v_mfma_f32_16x16x32_bf16 v[8:11], v[158:161], v[182:185], v[8:11]
	v_mfma_f32_16x16x32_bf16 v[4:7], v[150:153], v[190:193], v[4:7]
	v_mfma_f32_16x16x32_bf16 v[0:3], v[158:161], v[190:193], v[0:3]
	s_barrier
	s_setprio 0
	s_add_i32 s66, 0, 0x18000
	v_add_u32_e32 v124, s66, v235
	s_add_i32 s67, 0, 0x1c000
	ds_read_b128 v[130:133], v124
	ds_read_b128 v[134:137], v124 offset:1024
	ds_read_b128 v[138:141], v124 offset:2048
	ds_read_b128 v[142:145], v124 offset:3072
	v_add_u32_e32 v124, s67, v235
	ds_read_b128 v[146:149], v124
	ds_read_b128 v[150:153], v124 offset:1024
	ds_read_b128 v[154:157], v124 offset:2048
	ds_read_b128 v[158:161], v124 offset:3072
	s_add_u32 s4, s26, 0x480000
	s_addc_u32 s5, s27, 0
	s_mov_b32 m0, s38
	v_lshl_add_u64 v[124:125], s[4:5], 0, v[200:201]
	ds_read_b128 v[162:165], v236 offset:32768
	ds_read_b128 v[166:169], v236 offset:33792
	ds_read_b128 v[170:173], v236 offset:34816
	ds_read_b128 v[174:177], v236 offset:35840
	ds_read_b128 v[178:181], v236 offset:36864
	ds_read_b128 v[182:185], v236 offset:37888
	ds_read_b128 v[186:189], v236 offset:38912
	ds_read_b128 v[190:193], v236 offset:39936
	global_load_lds_dwordx4 v[124:125], off
	v_lshl_add_u64 v[124:125], s[4:5], 0, v[204:205]
	s_mov_b32 m0, s39
	s_nop 0
	global_load_lds_dwordx4 v[124:125], off
	s_waitcnt vmcnt(8)
	s_waitcnt lgkmcnt(0)
	s_setprio 1
	s_barrier
	v_mfma_f32_16x16x32_bf16 v[124:127], v[130:133], v[162:165], v[126:129]
	v_mfma_f32_16x16x32_bf16 v[120:123], v[138:141], v[162:165], v[120:123]
	v_mfma_f32_16x16x32_bf16 v[116:119], v[130:133], v[170:173], v[116:119]
	v_mfma_f32_16x16x32_bf16 v[112:115], v[138:141], v[170:173], v[112:115]
	v_mfma_f32_16x16x32_bf16 v[100:103], v[130:133], v[178:181], v[100:103]
	v_mfma_f32_16x16x32_bf16 v[96:99], v[138:141], v[178:181], v[96:99]
	v_mfma_f32_16x16x32_bf16 v[84:87], v[130:133], v[186:189], v[84:87]
	v_mfma_f32_16x16x32_bf16 v[80:83], v[138:141], v[186:189], v[80:83]
	v_mfma_f32_16x16x32_bf16 v[126:129], v[134:137], v[166:169], v[124:127]
	v_mfma_f32_16x16x32_bf16 v[122:125], v[142:145], v[166:169], v[120:123]
	v_mfma_f32_16x16x32_bf16 v[116:119], v[134:137], v[174:177], v[116:119]
	v_mfma_f32_16x16x32_bf16 v[112:115], v[142:145], v[174:177], v[112:115]
	v_mfma_f32_16x16x32_bf16 v[100:103], v[134:137], v[182:185], v[100:103]
	v_mfma_f32_16x16x32_bf16 v[96:99], v[142:145], v[182:185], v[96:99]
	v_mfma_f32_16x16x32_bf16 v[84:87], v[134:137], v[190:193], v[84:87]
	v_mfma_f32_16x16x32_bf16 v[80:83], v[142:145], v[190:193], v[80:83]
	v_mfma_f32_16x16x32_bf16 v[108:111], v[146:149], v[162:165], v[108:111]
	v_mfma_f32_16x16x32_bf16 v[104:107], v[154:157], v[162:165], v[104:107]
	v_mfma_f32_16x16x32_bf16 v[92:95], v[146:149], v[170:173], v[92:95]
	v_mfma_f32_16x16x32_bf16 v[88:91], v[154:157], v[170:173], v[88:91]
	v_mfma_f32_16x16x32_bf16 v[76:79], v[146:149], v[178:181], v[76:79]
	v_mfma_f32_16x16x32_bf16 v[72:75], v[154:157], v[178:181], v[72:75]
	v_mfma_f32_16x16x32_bf16 v[68:71], v[146:149], v[186:189], v[68:71]
	v_mfma_f32_16x16x32_bf16 v[64:67], v[154:157], v[186:189], v[64:67]
	v_mfma_f32_16x16x32_bf16 v[108:111], v[150:153], v[166:169], v[108:111]
	v_mfma_f32_16x16x32_bf16 v[104:107], v[158:161], v[166:169], v[104:107]
	v_mfma_f32_16x16x32_bf16 v[92:95], v[150:153], v[174:177], v[92:95]
	v_mfma_f32_16x16x32_bf16 v[88:91], v[158:161], v[174:177], v[88:91]
	v_mfma_f32_16x16x32_bf16 v[76:79], v[150:153], v[182:185], v[76:79]
	v_mfma_f32_16x16x32_bf16 v[72:75], v[158:161], v[182:185], v[72:75]
	v_mfma_f32_16x16x32_bf16 v[68:71], v[150:153], v[190:193], v[68:71]
	v_mfma_f32_16x16x32_bf16 v[64:67], v[158:161], v[190:193], v[64:67]
	s_barrier
; #define PG8_STAGE(bufoff, gbase, voff) do { _Pragma("unroll") for (int _i = 0; _i < 2; ++_i) \
;         __builtin_amdgcn_global_load_lds((const unsigned*)((const char*)(gbase) + (voff)[_i]), (LAS unsigned*)(lds + (bufoff) + ldsw + _i * 8192), 16, 0, 0); } while (0)
; #define PG8_LDA(dst, b, h) do { _Pragma("unroll") for (int m = 0; m < 4; ++m) _Pragma("unroll") for (int k = 0; k < 2; ++k) dst[m][k] = *(const LAS bf16x8*)(lds + PG8_SA(b, h) + aoff + m * 2048 + k * 1024); } while (0)
; #define PG8_MMA(ai, bj, At, Bt) do { __builtin_amdgcn_s_setprio(1); _Pragma("unroll") for (int m = 0; m < 4; ++m) _Pragma("unroll") for (int n = 0; n < 2; ++n) _Pragma("unroll") for (int k = 0; k < 2; ++k) \
;         acc[ai][bj][m][n] = __builtin_amdgcn_mfma_f32_16x16x32_bf16(Bt[n][k], At[m][k], acc[ai][bj][m][n], 0, 0, 0); __builtin_amdgcn_s_setprio(0); } while (0)
; #define PG8_WAIT_V(n) asm volatile("s_waitcnt vmcnt(" #n ")" ::: "memory")
; #define PG8_WAIT_L(n) asm volatile("s_waitcnt lgkmcnt(" #n ")" ::: "memory")
; #define PG8_BAR __builtin_amdgcn_s_barrier()
; #define PG8_SCHED __builtin_amdgcn_sched_barrier(0)
; template <class Epi, class Sched>
; __device__ __forceinline__ void gemm_stream(LAS unsigned char* lds, const int lda, const int ldb, const Sched& S, const Epi& E, const int wv) {
;     ...
;             PG8_LDA(At, 1, 1); PG8_STAGE(PG8_SB(1, 0), b3, voffB); PG8_STAGE(PG8_SB(1, 1), b3 + hstepB, voffB); PG8_STAGE(PG8_SA(1, 0), a3, voffA);
;             PG8_WAIT_V(8); PG8_WAIT_L(0); PG8_BAR; PG8_MMA(1, 0, At, B0); PG8_MMA(1, 1, At, B1); PG8_BAR; PG8_SCHED;
;         }
	s_setprio 0
	s_add_i32 s4, s66, s35
	v_lshl_add_u64 v[120:121], v[196:197], 0, s[78:79]
	s_mov_b32 m0, s4
	ds_read_b128 v[162:165], v236 offset:49152
	ds_read_b128 v[166:169], v236 offset:50176
	ds_read_b128 v[170:173], v236 offset:51200
	ds_read_b128 v[174:177], v236 offset:52224
	ds_read_b128 v[178:181], v236 offset:53248
	ds_read_b128 v[182:185], v236 offset:54272
	ds_read_b128 v[186:189], v236 offset:55296
	ds_read_b128 v[190:193], v236 offset:56320
	global_load_lds_dwordx4 v[120:121], off
	s_add_i32 m0, s4, 0x2000
	s_add_u32 s4, s24, 0x20080
	v_lshl_add_u64 v[120:121], v[198:199], 0, s[78:79]
	s_addc_u32 s5, s25, 0
	s_add_i32 s24, s67, s35
	global_load_lds_dwordx4 v[120:121], off
	v_lshl_add_u64 v[120:121], s[4:5], 0, v[202:203]
	s_mov_b32 m0, s24
	s_nop 0
	global_load_lds_dwordx4 v[120:121], off
	v_lshl_add_u64 v[120:121], s[4:5], 0, v[206:207]
	s_add_i32 m0, s24, 0x2000
	s_nop 0
	global_load_lds_dwordx4 v[120:121], off
	v_lshl_add_u64 v[120:121], v[212:213], 0, s[78:79]
	s_mov_b32 m0, s43
	s_nop 0
	global_load_lds_dwordx4 v[120:121], off
	v_lshl_add_u64 v[120:121], v[214:215], 0, s[78:79]
	s_mov_b32 m0, s44
	s_nop 0
	global_load_lds_dwordx4 v[120:121], off
	s_waitcnt vmcnt(8)
	s_waitcnt lgkmcnt(0)
	s_setprio 1
	s_barrier
	v_mfma_f32_16x16x32_bf16 v[60:63], v[130:133], v[162:165], v[60:63]
	v_mfma_f32_16x16x32_bf16 v[56:59], v[138:141], v[162:165], v[56:59]
	v_mfma_f32_16x16x32_bf16 v[52:55], v[130:133], v[170:173], v[52:55]
	v_mfma_f32_16x16x32_bf16 v[48:51], v[138:141], v[170:173], v[48:51]
	v_mfma_f32_16x16x32_bf16 v[36:39], v[130:133], v[178:181], v[36:39]
	v_mfma_f32_16x16x32_bf16 v[32:35], v[138:141], v[178:181], v[32:35]
	v_mfma_f32_16x16x32_bf16 v[20:23], v[130:133], v[186:189], v[20:23]
	v_mfma_f32_16x16x32_bf16 v[16:19], v[138:141], v[186:189], v[16:19]
	v_mfma_f32_16x16x32_bf16 v[60:63], v[134:137], v[166:169], v[60:63]
	v_mfma_f32_16x16x32_bf16 v[56:59], v[142:145], v[166:169], v[56:59]
	v_mfma_f32_16x16x32_bf16 v[52:55], v[134:137], v[174:177], v[52:55]
	v_mfma_f32_16x16x32_bf16 v[48:51], v[142:145], v[174:177], v[48:51]
	v_mfma_f32_16x16x32_bf16 v[36:39], v[134:137], v[182:185], v[36:39]
	v_mfma_f32_16x16x32_bf16 v[32:35], v[142:145], v[182:185], v[32:35]
	v_mfma_f32_16x16x32_bf16 v[20:23], v[134:137], v[190:193], v[20:23]
	v_mfma_f32_16x16x32_bf16 v[16:19], v[142:145], v[190:193], v[16:19]
	v_mfma_f32_16x16x32_bf16 v[44:47], v[146:149], v[162:165], v[44:47]
	v_mfma_f32_16x16x32_bf16 v[40:43], v[154:157], v[162:165], v[40:43]
	v_mfma_f32_16x16x32_bf16 v[28:31], v[146:149], v[170:173], v[28:31]
	v_mfma_f32_16x16x32_bf16 v[24:27], v[154:157], v[170:173], v[24:27]
	v_mfma_f32_16x16x32_bf16 v[12:15], v[146:149], v[178:181], v[12:15]
	v_mfma_f32_16x16x32_bf16 v[8:11], v[154:157], v[178:181], v[8:11]
	v_mfma_f32_16x16x32_bf16 v[4:7], v[146:149], v[186:189], v[4:7]
	v_mfma_f32_16x16x32_bf16 v[0:3], v[154:157], v[186:189], v[0:3]
	v_mfma_f32_16x16x32_bf16 v[44:47], v[150:153], v[166:169], v[44:47]
	v_mfma_f32_16x16x32_bf16 v[40:43], v[158:161], v[166:169], v[40:43]
	v_mfma_f32_16x16x32_bf16 v[28:31], v[150:153], v[174:177], v[28:31]
	v_mfma_f32_16x16x32_bf16 v[24:27], v[158:161], v[174:177], v[24:27]
	v_mfma_f32_16x16x32_bf16 v[12:15], v[150:153], v[182:185], v[12:15]
	v_mfma_f32_16x16x32_bf16 v[8:11], v[158:161], v[182:185], v[8:11]
	v_mfma_f32_16x16x32_bf16 v[4:7], v[150:153], v[190:193], v[4:7]
	v_mfma_f32_16x16x32_bf16 v[0:3], v[158:161], v[190:193], v[0:3]
	s_barrier
	s_setprio 0
	s_add_u32 s61, s61, 0x100
	s_addc_u32 s62, s62, 0
	s_cmp_ge_i32 s63, s56
	s_mov_b64 s[4:5], s[22:23]
	s_mov_b32 s24, s63
	s_cbranch_scc0 .LBB0_496
	v_mov_b32_e32 v244, 0x3d800000
	s_and_b64 vcc, exec, s[12:13]
	s_cbranch_vccz .LBB0_499
	s_barrier

; #define PG8_STAGE(bufoff, gbase, voff) do { _Pragma("unroll") for (int _i = 0; _i < 2; ++_i) \
;         __builtin_amdgcn_global_load_lds((const unsigned*)((const char*)(gbase) + (voff)[_i]), (LAS unsigned*)(lds + (bufoff) + ldsw + _i * 8192), 16, 0, 0); } while (0)
; #define PG8_LDA(dst, b, h) do { _Pragma("unroll") for (int m = 0; m < 4; ++m) _Pragma("unroll") for (int k = 0; k < 2; ++k) dst[m][k] = *(const LAS bf16x8*)(lds + PG8_SA(b, h) + aoff + m * 2048 + k * 1024); } while (0)
; #define PG8_LDB(dst, b, h) do { _Pragma("unroll") for (int n = 0; n < 2; ++n) _Pragma("unroll") for (int k = 0; k < 2; ++k) dst[n][k] = *(const LAS bf16x8*)(lds + PG8_SB(b, h) + boff + n * 2048 + k * 1024); } while (0)
; #define PG8_MMA(ai, bj, At, Bt) do { __builtin_amdgcn_s_setprio(1); _Pragma("unroll") for (int m = 0; m < 4; ++m) _Pragma("unroll") for (int n = 0; n < 2; ++n) _Pragma("unroll") for (int k = 0; k < 2; ++k) \
;         acc[ai][bj][m][n] = __builtin_amdgcn_mfma_f32_16x16x32_bf16(Bt[n][k], At[m][k], acc[ai][bj][m][n], 0, 0, 0); __builtin_amdgcn_s_setprio(0); } while (0)
; #define PG8_WAIT_V(n) asm volatile("s_waitcnt vmcnt(" #n ")" ::: "memory")
; #define PG8_WAIT_L(n) asm volatile("s_waitcnt lgkmcnt(" #n ")" ::: "memory")
; #define PG8_BAR __builtin_amdgcn_s_barrier()
; #define PG8_SCHED __builtin_amdgcn_sched_barrier(0)
; template <class Epi, class Sched>
; __device__ __forceinline__ void gemm_stream(LAS unsigned char* lds, const int lda, const int ldb, const Sched& S, const Epi& E, const int wv) {
;     ...
;         for (int t = 0; t < nt; t += 2) {
;             const bool last = (t == nt - 2);
;             const char* a1 = cA + (size_t)(t + 1) * kstep;
;             const char* a2 = last ? nA : cA + (size_t)(t + 2) * kstep; const char* b2 = last ? nB : cB + (size_t)(t + 2) * kstep;
;             const char* a3 = a2 + kstep; const char* b3 = b2 + kstep;
;             PG8_LDB(B0, 0, 0); PG8_LDB(B1, 0, 1); PG8_SCHED; PG8_LDA(At, 0, 0); PG8_STAGE(PG8_SA(1, 1), a1 + hstepA, voffA);
;             PG8_WAIT_V(8); PG8_WAIT_L(0); PG8_BAR; PG8_MMA(0, 0, At, B0); PG8_MMA(0, 1, At, B1); PG8_BAR; PG8_SCHED;
;             PG8_LDA(At, 0, 1); PG8_STAGE(PG8_SB(0, 0), b2, voffB); PG8_STAGE(PG8_SB(0, 1), b2 + hstepB, voffB); PG8_STAGE(PG8_SA(0, 0), a2, voffA);
;             PG8_WAIT_V(8); PG8_WAIT_L(0); PG8_BAR; PG8_MMA(1, 0, At, B0); PG8_MMA(1, 1, At, B1); PG8_BAR; PG8_SCHED;
.LBB0_600:
	s_add_u32 s22, s20, 0xfff80080
	s_addc_u32 s23, s21, -1
	s_add_i32 s47, 0, 0x10000
	s_cmp_eq_u32 s46, 28
	s_cselect_b32 s25, s17, s23
	s_cselect_b32 s24, s16, s22
	s_cselect_b32 s23, s19, s15
	s_cselect_b32 s22, s18, s13
	s_add_i32 s50, 0, 0x14000
	v_add_u32_e32 v140, s47, v165
	v_add_u32_e32 v167, s50, v165
	ds_read_b128 v[128:131], v140
	ds_read_b128 v[132:135], v140 offset:1024
	ds_read_b128 v[136:139], v140 offset:2048
	ds_read_b128 v[140:143], v140 offset:3072
	ds_read_b128 v[156:159], v167
	ds_read_b128 v[160:163], v167 offset:1024
	ds_read_b128 v[168:171], v167 offset:2048
	ds_read_b128 v[172:175], v167 offset:3072
	v_lshl_add_u64 v[192:193], s[20:21], 0, v[152:153]
	s_add_i32 m0, s31, 0xc000
	ds_read_b128 v[176:179], v166
	ds_read_b128 v[180:183], v166 offset:1024
	ds_read_b128 v[184:187], v166 offset:2048
	ds_read_b128 v[188:191], v166 offset:3072
	ds_read_b128 v[200:203], v166 offset:4096
	ds_read_b128 v[204:207], v166 offset:5120
	ds_read_b128 v[208:211], v166 offset:6144
	ds_read_b128 v[212:215], v166 offset:7168
	global_load_lds_dwordx4 v[192:193], off
	v_lshl_add_u64 v[192:193], s[20:21], 0, v[154:155]
	s_add_i32 m0, s31, 0xe000
	s_nop 0
	global_load_lds_dwordx4 v[192:193], off
	s_waitcnt vmcnt(8)
	s_waitcnt lgkmcnt(0)
	s_setprio 1
	s_barrier
	v_mfma_f32_16x16x32_bf16 v[124:127], v[128:131], v[176:179], v[124:127]
	v_mfma_f32_16x16x32_bf16 v[120:123], v[136:139], v[176:179], v[120:123]
	v_mfma_f32_16x16x32_bf16 v[108:111], v[128:131], v[184:187], v[108:111]
	v_mfma_f32_16x16x32_bf16 v[104:107], v[136:139], v[184:187], v[104:107]
	v_mfma_f32_16x16x32_bf16 v[92:95], v[128:131], v[200:203], v[92:95]
	v_mfma_f32_16x16x32_bf16 v[88:91], v[136:139], v[200:203], v[88:91]
	v_mfma_f32_16x16x32_bf16 v[76:79], v[128:131], v[208:211], v[76:79]
	v_mfma_f32_16x16x32_bf16 v[72:75], v[136:139], v[208:211], v[72:75]
	v_mfma_f32_16x16x32_bf16 v[124:127], v[132:135], v[180:183], v[124:127]
	v_mfma_f32_16x16x32_bf16 v[120:123], v[140:143], v[180:183], v[120:123]
	v_mfma_f32_16x16x32_bf16 v[108:111], v[132:135], v[188:191], v[108:111]
	v_mfma_f32_16x16x32_bf16 v[104:107], v[140:143], v[188:191], v[104:107]
	v_mfma_f32_16x16x32_bf16 v[92:95], v[132:135], v[204:207], v[92:95]
	v_mfma_f32_16x16x32_bf16 v[88:91], v[140:143], v[204:207], v[88:91]
	v_mfma_f32_16x16x32_bf16 v[76:79], v[132:135], v[212:215], v[76:79]
	v_mfma_f32_16x16x32_bf16 v[72:75], v[140:143], v[212:215], v[72:75]
	v_mfma_f32_16x16x32_bf16 v[116:119], v[156:159], v[176:179], v[116:119]
	v_mfma_f32_16x16x32_bf16 v[112:115], v[168:171], v[176:179], v[112:115]
	v_mfma_f32_16x16x32_bf16 v[100:103], v[156:159], v[184:187], v[100:103]
	v_mfma_f32_16x16x32_bf16 v[96:99], v[168:171], v[184:187], v[96:99]
	v_mfma_f32_16x16x32_bf16 v[84:87], v[156:159], v[200:203], v[84:87]
	v_mfma_f32_16x16x32_bf16 v[80:83], v[168:171], v[200:203], v[80:83]
	v_mfma_f32_16x16x32_bf16 v[68:71], v[156:159], v[208:211], v[68:71]
	v_mfma_f32_16x16x32_bf16 v[64:67], v[168:171], v[208:211], v[64:67]
	v_mfma_f32_16x16x32_bf16 v[116:119], v[160:163], v[180:183], v[116:119]
	v_mfma_f32_16x16x32_bf16 v[112:115], v[172:175], v[180:183], v[112:115]
	v_mfma_f32_16x16x32_bf16 v[100:103], v[160:163], v[188:191], v[100:103]
	v_mfma_f32_16x16x32_bf16 v[96:99], v[172:175], v[188:191], v[96:99]
	v_mfma_f32_16x16x32_bf16 v[84:87], v[160:163], v[204:207], v[84:87]
	v_mfma_f32_16x16x32_bf16 v[80:83], v[172:175], v[204:207], v[80:83]
	v_mfma_f32_16x16x32_bf16 v[68:71], v[160:163], v[212:215], v[68:71]
	v_mfma_f32_16x16x32_bf16 v[64:67], v[172:175], v[212:215], v[64:67]
	s_barrier
	s_setprio 0
	s_add_i32 s47, s47, s30
	v_lshl_add_u64 v[192:193], s[22:23], 0, v[148:149]
	s_mov_b32 m0, s47
	ds_read_b128 v[176:179], v166 offset:16384
	ds_read_b128 v[180:183], v166 offset:17408
	ds_read_b128 v[184:187], v166 offset:18432
	ds_read_b128 v[188:191], v166 offset:19456
	ds_read_b128 v[200:203], v166 offset:20480
	ds_read_b128 v[204:207], v166 offset:21504
	ds_read_b128 v[208:211], v166 offset:22528
	ds_read_b128 v[212:215], v166 offset:23552
	global_load_lds_dwordx4 v[192:193], off
	s_add_i32 m0, s47, 0x2000
	s_add_u32 s48, s22, 0x20000
	v_lshl_add_u64 v[196:197], s[22:23], 0, v[144:145]
	s_addc_u32 s49, s23, 0
	s_add_i32 s47, s50, s30
	global_load_lds_dwordx4 v[196:197], off
	v_lshl_add_u64 v[198:199], s[48:49], 0, v[148:149]
	s_mov_b32 m0, s47
	v_lshl_add_u64 v[216:217], s[24:25], 0, v[146:147]
	global_load_lds_dwordx4 v[198:199], off
	v_lshl_add_u64 v[198:199], s[48:49], 0, v[144:145]
	s_add_i32 m0, s47, 0x2000
	s_nop 0
	global_load_lds_dwordx4 v[198:199], off
	v_lshl_add_u64 v[198:199], s[24:25], 0, v[150:151]
	s_mov_b32 m0, s31
	s_nop 0
	global_load_lds_dwordx4 v[198:199], off
	s_mov_b32 m0, s34
	s_nop 0
	global_load_lds_dwordx4 v[216:217], off
	s_waitcnt vmcnt(8)
	s_waitcnt lgkmcnt(0)
	s_setprio 1
	s_barrier
; #define PG8_STAGE(bufoff, gbase, voff) do { _Pragma("unroll") for (int _i = 0; _i < 2; ++_i) \
;         __builtin_amdgcn_global_load_lds((const unsigned*)((const char*)(gbase) + (voff)[_i]), (LAS unsigned*)(lds + (bufoff) + ldsw + _i * 8192), 16, 0, 0); } while (0)
; #define PG8_LDA(dst, b, h) do { _Pragma("unroll") for (int m = 0; m < 4; ++m) _Pragma("unroll") for (int k = 0; k < 2; ++k) dst[m][k] = *(const LAS bf16x8*)(lds + PG8_SA(b, h) + aoff + m * 2048 + k * 1024); } while (0)
; #define PG8_LDB(dst, b, h) do { _Pragma("unroll") for (int n = 0; n < 2; ++n) _Pragma("unroll") for (int k = 0; k < 2; ++k) dst[n][k] = *(const LAS bf16x8*)(lds + PG8_SB(b, h) + boff + n * 2048 + k * 1024); } while (0)
; #define PG8_MMA(ai, bj, At, Bt) do { __builtin_amdgcn_s_setprio(1); _Pragma("unroll") for (int m = 0; m < 4; ++m) _Pragma("unroll") for (int n = 0; n < 2; ++n) _Pragma("unroll") for (int k = 0; k < 2; ++k) \
;         acc[ai][bj][m][n] = __builtin_amdgcn_mfma_f32_16x16x32_bf16(Bt[n][k], At[m][k], acc[ai][bj][m][n], 0, 0, 0); __builtin_amdgcn_s_setprio(0); } while (0)
; #define PG8_WAIT_V(n) asm volatile("s_waitcnt vmcnt(" #n ")" ::: "memory")
; #define PG8_WAIT_L(n) asm volatile("s_waitcnt lgkmcnt(" #n ")" ::: "memory")
; #define PG8_BAR __builtin_amdgcn_s_barrier()
; #define PG8_SCHED __builtin_amdgcn_sched_barrier(0)
; template <class Epi, class Sched>
; __device__ __forceinline__ void gemm_stream(LAS unsigned char* lds, const int lda, const int ldb, const Sched& S, const Epi& E, const int wv) {
;     ...
;             PG8_WAIT_V(8); PG8_WAIT_L(0); PG8_BAR; PG8_MMA(1, 0, At, B0); PG8_MMA(1, 1, At, B1); PG8_BAR; PG8_SCHED;
;             PG8_LDB(B0, 1, 0); PG8_LDB(B1, 1, 1); PG8_SCHED; PG8_LDA(At, 1, 0); PG8_STAGE(PG8_SA(0, 1), a2 + hstepA, voffA);
;             PG8_WAIT_V(8); PG8_WAIT_L(0); PG8_BAR; PG8_MMA(0, 0, At, B0); PG8_MMA(0, 1, At, B1); PG8_BAR; PG8_SCHED;
;             PG8_LDA(At, 1, 1); PG8_STAGE(PG8_SB(1, 0), b3, voffB); PG8_STAGE(PG8_SB(1, 1), b3 + hstepB, voffB); PG8_STAGE(PG8_SA(1, 0), a3, voffA);
;             PG8_WAIT_V(8); PG8_WAIT_L(0); PG8_BAR; PG8_MMA(1, 0, At, B0); PG8_MMA(1, 1, At, B1); PG8_BAR; PG8_SCHED;
	v_mfma_f32_16x16x32_bf16 v[60:63], v[128:131], v[176:179], v[60:63]
	v_mfma_f32_16x16x32_bf16 v[56:59], v[136:139], v[176:179], v[56:59]
	v_mfma_f32_16x16x32_bf16 v[44:47], v[128:131], v[184:187], v[44:47]
	v_mfma_f32_16x16x32_bf16 v[40:43], v[136:139], v[184:187], v[40:43]
	v_mfma_f32_16x16x32_bf16 v[28:31], v[128:131], v[200:203], v[28:31]
	v_mfma_f32_16x16x32_bf16 v[24:27], v[136:139], v[200:203], v[24:27]
	v_mfma_f32_16x16x32_bf16 v[12:15], v[128:131], v[208:211], v[12:15]
	v_mfma_f32_16x16x32_bf16 v[8:11], v[136:139], v[208:211], v[8:11]
	v_mfma_f32_16x16x32_bf16 v[60:63], v[132:135], v[180:183], v[60:63]
	v_mfma_f32_16x16x32_bf16 v[56:59], v[140:143], v[180:183], v[56:59]
	v_mfma_f32_16x16x32_bf16 v[44:47], v[132:135], v[188:191], v[44:47]
	v_mfma_f32_16x16x32_bf16 v[40:43], v[140:143], v[188:191], v[40:43]
	v_mfma_f32_16x16x32_bf16 v[28:31], v[132:135], v[204:207], v[28:31]
	v_mfma_f32_16x16x32_bf16 v[24:27], v[140:143], v[204:207], v[24:27]
	v_mfma_f32_16x16x32_bf16 v[12:15], v[132:135], v[212:215], v[12:15]
	v_mfma_f32_16x16x32_bf16 v[8:11], v[140:143], v[212:215], v[8:11]
	v_mfma_f32_16x16x32_bf16 v[52:55], v[156:159], v[176:179], v[52:55]
	v_mfma_f32_16x16x32_bf16 v[48:51], v[168:171], v[176:179], v[48:51]
	v_mfma_f32_16x16x32_bf16 v[36:39], v[156:159], v[184:187], v[36:39]
	v_mfma_f32_16x16x32_bf16 v[32:35], v[168:171], v[184:187], v[32:35]
	v_mfma_f32_16x16x32_bf16 v[20:23], v[156:159], v[200:203], v[20:23]
	v_mfma_f32_16x16x32_bf16 v[16:19], v[168:171], v[200:203], v[16:19]
	v_mfma_f32_16x16x32_bf16 v[4:7], v[156:159], v[208:211], v[4:7]
	v_mfma_f32_16x16x32_bf16 v[0:3], v[168:171], v[208:211], v[0:3]
	v_mfma_f32_16x16x32_bf16 v[52:55], v[160:163], v[180:183], v[52:55]
	v_mfma_f32_16x16x32_bf16 v[48:51], v[172:175], v[180:183], v[48:51]
	v_mfma_f32_16x16x32_bf16 v[36:39], v[160:163], v[188:191], v[36:39]
	v_mfma_f32_16x16x32_bf16 v[32:35], v[172:175], v[188:191], v[32:35]
	v_mfma_f32_16x16x32_bf16 v[20:23], v[160:163], v[204:207], v[20:23]
	v_mfma_f32_16x16x32_bf16 v[16:19], v[172:175], v[204:207], v[16:19]
	v_mfma_f32_16x16x32_bf16 v[4:7], v[160:163], v[212:215], v[4:7]
	v_mfma_f32_16x16x32_bf16 v[0:3], v[172:175], v[212:215], v[0:3]
	s_barrier
	s_setprio 0
	s_add_i32 s47, 0, 0x18000
	s_add_i32 s48, 0, 0x1c000
	v_add_u32_e32 v140, s47, v165
	v_add_u32_e32 v167, s48, v165
	ds_read_b128 v[128:131], v140
	ds_read_b128 v[132:135], v140 offset:1024
	ds_read_b128 v[136:139], v140 offset:2048
	ds_read_b128 v[140:143], v140 offset:3072
	ds_read_b128 v[156:159], v167
	ds_read_b128 v[160:163], v167 offset:1024
	ds_read_b128 v[168:171], v167 offset:2048
	ds_read_b128 v[172:175], v167 offset:3072
	s_add_u32 s24, s24, 0x80000
	s_addc_u32 s25, s25, 0
	s_mov_b32 m0, s35
	v_lshl_add_u64 v[218:219], s[24:25], 0, v[150:151]
	ds_read_b128 v[176:179], v166 offset:32768
	ds_read_b128 v[180:183], v166 offset:33792
	ds_read_b128 v[184:187], v166 offset:34816
	ds_read_b128 v[188:191], v166 offset:35840
	ds_read_b128 v[200:203], v166 offset:36864
	ds_read_b128 v[204:207], v166 offset:37888
	ds_read_b128 v[208:211], v166 offset:38912
	ds_read_b128 v[212:215], v166 offset:39936
	global_load_lds_dwordx4 v[218:219], off
	v_lshl_add_u64 v[218:219], s[24:25], 0, v[146:147]
	s_mov_b32 m0, s36
	s_nop 0
	global_load_lds_dwordx4 v[218:219], off
	s_waitcnt vmcnt(8)
	s_waitcnt lgkmcnt(0)
	s_setprio 1
	s_barrier
	v_mfma_f32_16x16x32_bf16 v[124:127], v[128:131], v[176:179], v[124:127]
	v_mfma_f32_16x16x32_bf16 v[120:123], v[136:139], v[176:179], v[120:123]
	v_mfma_f32_16x16x32_bf16 v[108:111], v[128:131], v[184:187], v[108:111]
	v_mfma_f32_16x16x32_bf16 v[104:107], v[136:139], v[184:187], v[104:107]
	v_mfma_f32_16x16x32_bf16 v[92:95], v[128:131], v[200:203], v[92:95]
	v_mfma_f32_16x16x32_bf16 v[88:91], v[136:139], v[200:203], v[88:91]
	v_mfma_f32_16x16x32_bf16 v[76:79], v[128:131], v[208:211], v[76:79]
	v_mfma_f32_16x16x32_bf16 v[72:75], v[136:139], v[208:211], v[72:75]
	v_mfma_f32_16x16x32_bf16 v[124:127], v[132:135], v[180:183], v[124:127]
	v_mfma_f32_16x16x32_bf16 v[120:123], v[140:143], v[180:183], v[120:123]
	v_mfma_f32_16x16x32_bf16 v[108:111], v[132:135], v[188:191], v[108:111]
	v_mfma_f32_16x16x32_bf16 v[104:107], v[140:143], v[188:191], v[104:107]
	v_mfma_f32_16x16x32_bf16 v[92:95], v[132:135], v[204:207], v[92:95]
	v_mfma_f32_16x16x32_bf16 v[88:91], v[140:143], v[204:207], v[88:91]
	v_mfma_f32_16x16x32_bf16 v[76:79], v[132:135], v[212:215], v[76:79]
	v_mfma_f32_16x16x32_bf16 v[72:75], v[140:143], v[212:215], v[72:75]
	v_mfma_f32_16x16x32_bf16 v[116:119], v[156:159], v[176:179], v[116:119]
	v_mfma_f32_16x16x32_bf16 v[112:115], v[168:171], v[176:179], v[112:115]
	v_mfma_f32_16x16x32_bf16 v[100:103], v[156:159], v[184:187], v[100:103]
	v_mfma_f32_16x16x32_bf16 v[96:99], v[168:171], v[184:187], v[96:99]
	v_mfma_f32_16x16x32_bf16 v[84:87], v[156:159], v[200:203], v[84:87]
	v_mfma_f32_16x16x32_bf16 v[80:83], v[168:171], v[200:203], v[80:83]
	v_mfma_f32_16x16x32_bf16 v[68:71], v[156:159], v[208:211], v[68:71]
	v_mfma_f32_16x16x32_bf16 v[64:67], v[168:171], v[208:211], v[64:67]
	v_mfma_f32_16x16x32_bf16 v[116:119], v[160:163], v[180:183], v[116:119]
	v_mfma_f32_16x16x32_bf16 v[112:115], v[172:175], v[180:183], v[112:115]
	v_mfma_f32_16x16x32_bf16 v[100:103], v[160:163], v[188:191], v[100:103]
	v_mfma_f32_16x16x32_bf16 v[96:99], v[172:175], v[188:191], v[96:99]
	v_mfma_f32_16x16x32_bf16 v[84:87], v[160:163], v[204:207], v[84:87]
	v_mfma_f32_16x16x32_bf16 v[80:83], v[172:175], v[204:207], v[80:83]
	v_mfma_f32_16x16x32_bf16 v[68:71], v[160:163], v[212:215], v[68:71]
	v_mfma_f32_16x16x32_bf16 v[64:67], v[172:175], v[212:215], v[64:67]
	s_barrier
; #define PG8_STAGE(bufoff, gbase, voff) do { _Pragma("unroll") for (int _i = 0; _i < 2; ++_i) \
;         __builtin_amdgcn_global_load_lds((const unsigned*)((const char*)(gbase) + (voff)[_i]), (LAS unsigned*)(lds + (bufoff) + ldsw + _i * 8192), 16, 0, 0); } while (0)
; #define PG8_LDA(dst, b, h) do { _Pragma("unroll") for (int m = 0; m < 4; ++m) _Pragma("unroll") for (int k = 0; k < 2; ++k) dst[m][k] = *(const LAS bf16x8*)(lds + PG8_SA(b, h) + aoff + m * 2048 + k * 1024); } while (0)
; #define PG8_MMA(ai, bj, At, Bt) do { __builtin_amdgcn_s_setprio(1); _Pragma("unroll") for (int m = 0; m < 4; ++m) _Pragma("unroll") for (int n = 0; n < 2; ++n) _Pragma("unroll") for (int k = 0; k < 2; ++k) \
;         acc[ai][bj][m][n] = __builtin_amdgcn_mfma_f32_16x16x32_bf16(Bt[n][k], At[m][k], acc[ai][bj][m][n], 0, 0, 0); __builtin_amdgcn_s_setprio(0); } while (0)
; #define PG8_WAIT_V(n) asm volatile("s_waitcnt vmcnt(" #n ")" ::: "memory")
; #define PG8_WAIT_L(n) asm volatile("s_waitcnt lgkmcnt(" #n ")" ::: "memory")
; #define PG8_BAR __builtin_amdgcn_s_barrier()
; #define PG8_SCHED __builtin_amdgcn_sched_barrier(0)
; template <class Epi, class Sched>
; __device__ __forceinline__ void gemm_stream(LAS unsigned char* lds, const int lda, const int ldb, const Sched& S, const Epi& E, const int wv) {
;     ...
;             PG8_LDA(At, 1, 1); PG8_STAGE(PG8_SB(1, 0), b3, voffB); PG8_STAGE(PG8_SB(1, 1), b3 + hstepB, voffB); PG8_STAGE(PG8_SA(1, 0), a3, voffA);
;             PG8_WAIT_V(8); PG8_WAIT_L(0); PG8_BAR; PG8_MMA(1, 0, At, B0); PG8_MMA(1, 1, At, B1); PG8_BAR; PG8_SCHED;
;         }
	s_setprio 0
	s_add_i32 s24, s47, s30
	v_lshl_add_u64 v[192:193], v[192:193], 0, s[78:79]
	s_mov_b32 m0, s24
	ds_read_b128 v[176:179], v166 offset:49152
	ds_read_b128 v[180:183], v166 offset:50176
	ds_read_b128 v[184:187], v166 offset:51200
	ds_read_b128 v[188:191], v166 offset:52224
	ds_read_b128 v[200:203], v166 offset:53248
	ds_read_b128 v[204:207], v166 offset:54272
	ds_read_b128 v[208:211], v166 offset:55296
	ds_read_b128 v[212:215], v166 offset:56320
	global_load_lds_dwordx4 v[192:193], off
	s_add_i32 m0, s24, 0x2000
	s_add_u32 s22, s22, 0x20080
	v_lshl_add_u64 v[192:193], v[196:197], 0, s[78:79]
	s_addc_u32 s23, s23, 0
	s_add_i32 s24, s48, s30
	global_load_lds_dwordx4 v[192:193], off
	v_lshl_add_u64 v[192:193], s[22:23], 0, v[148:149]
	s_mov_b32 m0, s24
	s_nop 0
	global_load_lds_dwordx4 v[192:193], off
	v_lshl_add_u64 v[192:193], s[22:23], 0, v[144:145]
	s_add_i32 m0, s24, 0x2000
	s_nop 0
	global_load_lds_dwordx4 v[192:193], off
	v_lshl_add_u64 v[192:193], v[198:199], 0, s[78:79]
	s_mov_b32 m0, s40
	s_nop 0
	global_load_lds_dwordx4 v[192:193], off
	v_lshl_add_u64 v[192:193], v[216:217], 0, s[78:79]
	s_mov_b32 m0, s41
	s_nop 0
	global_load_lds_dwordx4 v[192:193], off
	s_waitcnt vmcnt(8)
	s_waitcnt lgkmcnt(0)
	s_setprio 1
	s_barrier
	v_mfma_f32_16x16x32_bf16 v[60:63], v[128:131], v[176:179], v[60:63]
	v_mfma_f32_16x16x32_bf16 v[56:59], v[136:139], v[176:179], v[56:59]
	v_mfma_f32_16x16x32_bf16 v[44:47], v[128:131], v[184:187], v[44:47]
	v_mfma_f32_16x16x32_bf16 v[40:43], v[136:139], v[184:187], v[40:43]
	v_mfma_f32_16x16x32_bf16 v[28:31], v[128:131], v[200:203], v[28:31]
	v_mfma_f32_16x16x32_bf16 v[24:27], v[136:139], v[200:203], v[24:27]
	v_mfma_f32_16x16x32_bf16 v[12:15], v[128:131], v[208:211], v[12:15]
	v_mfma_f32_16x16x32_bf16 v[8:11], v[136:139], v[208:211], v[8:11]
	v_mfma_f32_16x16x32_bf16 v[60:63], v[132:135], v[180:183], v[60:63]
	v_mfma_f32_16x16x32_bf16 v[56:59], v[140:143], v[180:183], v[56:59]
	v_mfma_f32_16x16x32_bf16 v[44:47], v[132:135], v[188:191], v[44:47]
	v_mfma_f32_16x16x32_bf16 v[40:43], v[140:143], v[188:191], v[40:43]
	v_mfma_f32_16x16x32_bf16 v[28:31], v[132:135], v[204:207], v[28:31]
	v_mfma_f32_16x16x32_bf16 v[24:27], v[140:143], v[204:207], v[24:27]
	v_mfma_f32_16x16x32_bf16 v[12:15], v[132:135], v[212:215], v[12:15]
	v_mfma_f32_16x16x32_bf16 v[8:11], v[140:143], v[212:215], v[8:11]
	v_mfma_f32_16x16x32_bf16 v[52:55], v[156:159], v[176:179], v[52:55]
	v_mfma_f32_16x16x32_bf16 v[48:51], v[168:171], v[176:179], v[48:51]
	v_mfma_f32_16x16x32_bf16 v[36:39], v[156:159], v[184:187], v[36:39]
	v_mfma_f32_16x16x32_bf16 v[32:35], v[168:171], v[184:187], v[32:35]
	v_mfma_f32_16x16x32_bf16 v[20:23], v[156:159], v[200:203], v[20:23]
	v_mfma_f32_16x16x32_bf16 v[16:19], v[168:171], v[200:203], v[16:19]
	v_mfma_f32_16x16x32_bf16 v[4:7], v[156:159], v[208:211], v[4:7]
	v_mfma_f32_16x16x32_bf16 v[0:3], v[168:171], v[208:211], v[0:3]
	v_mfma_f32_16x16x32_bf16 v[52:55], v[160:163], v[180:183], v[52:55]
	v_mfma_f32_16x16x32_bf16 v[48:51], v[172:175], v[180:183], v[48:51]
	v_mfma_f32_16x16x32_bf16 v[36:39], v[160:163], v[188:191], v[36:39]
	v_mfma_f32_16x16x32_bf16 v[32:35], v[172:175], v[188:191], v[32:35]
	v_mfma_f32_16x16x32_bf16 v[20:23], v[160:163], v[204:207], v[20:23]
	v_mfma_f32_16x16x32_bf16 v[16:19], v[172:175], v[204:207], v[16:19]
	v_mfma_f32_16x16x32_bf16 v[4:7], v[160:163], v[212:215], v[4:7]
	v_mfma_f32_16x16x32_bf16 v[0:3], v[172:175], v[212:215], v[0:3]
	s_barrier
	s_setprio 0
	s_add_i32 s46, s46, 2
	s_add_u32 s20, s20, 0x100
	s_addc_u32 s21, s21, 0
	s_add_u32 s13, s13, 0x100
	s_addc_u32 s15, s15, 0
	s_cmp_gt_u32 s46, 29
	s_cbranch_scc0 .LBB0_600
	s_and_b64 vcc, exec, s[6:7]
	s_cbranch_vccz .LBB0_603
	s_barrier
